# LRU passes 1 and 2: a/b staging stores paired into ds_write2st64_b32 (24 -> 12 per item), u-value reads hoisted; fewer LDS store-path transfers
# speedup vs baseline: 1.0117x; 1.0002x over previous
.LBB0_301:
	s_waitcnt lgkmcnt(0)
	s_barrier
	ds_read_b128 v[110:113], v135
	ds_read_b128 v[114:117], v135 offset:4352
	ds_read_b128 v[122:125], v135 offset:8704
	ds_read_b128 v[194:197], v135 offset:13056
	s_waitcnt lgkmcnt(3)
	v_mfma_f32_16x16x32_bf16 v[118:121], v[110:113], v[0:3], 0
	v_mfma_f32_16x16x32_bf16 v[110:113], v[110:113], v[8:11], 0
	ds_read_b128 v[206:209], v135 offset:64
	s_waitcnt lgkmcnt(3)
	v_mfma_f32_16x16x32_bf16 v[198:201], v[114:117], v[0:3], 0
	v_mfma_f32_16x16x32_bf16 v[114:117], v[114:117], v[8:11], 0
	ds_read_b128 v[214:217], v135 offset:4416
	s_waitcnt lgkmcnt(3)
	v_mfma_f32_16x16x32_bf16 v[210:213], v[122:125], v[0:3], 0
	v_mfma_f32_16x16x32_bf16 v[122:125], v[122:125], v[8:11], 0
	ds_read_b128 v[222:225], v135 offset:8768
	s_waitcnt lgkmcnt(3)
	v_mfma_f32_16x16x32_bf16 v[218:221], v[194:197], v[0:3], 0
	v_mfma_f32_16x16x32_bf16 v[194:197], v[194:197], v[8:11], 0
	ds_read_b128 v[226:229], v135 offset:13120
	s_waitcnt lgkmcnt(3)
	v_mfma_f32_16x16x32_bf16 v[118:121], v[206:209], v[4:7], v[118:121]
	v_mfma_f32_16x16x32_bf16 v[110:113], v[206:209], v[12:15], v[110:113]
	ds_read_b128 v[206:209], v135 offset:128
	s_waitcnt lgkmcnt(3)
	v_mfma_f32_16x16x32_bf16 v[198:201], v[214:217], v[4:7], v[198:201]
	v_mfma_f32_16x16x32_bf16 v[114:117], v[214:217], v[12:15], v[114:117]
	ds_read_b128 v[214:217], v135 offset:4480
	s_waitcnt lgkmcnt(3)
	v_mfma_f32_16x16x32_bf16 v[210:213], v[222:225], v[4:7], v[210:213]
	v_mfma_f32_16x16x32_bf16 v[122:125], v[222:225], v[12:15], v[122:125]
	ds_read_b128 v[222:225], v135 offset:8832
	s_waitcnt lgkmcnt(3)
	v_mfma_f32_16x16x32_bf16 v[218:221], v[226:229], v[4:7], v[218:221]
	v_mfma_f32_16x16x32_bf16 v[194:197], v[226:229], v[12:15], v[194:197]
	ds_read_b128 v[226:229], v135 offset:13184
	s_waitcnt lgkmcnt(3)
	v_mfma_f32_16x16x32_bf16 v[118:121], v[206:209], v[16:19], v[118:121]
	v_mfma_f32_16x16x32_bf16 v[110:113], v[206:209], v[28:31], v[110:113]
	ds_read_b128 v[206:209], v135 offset:192
	s_waitcnt lgkmcnt(3)
	v_mfma_f32_16x16x32_bf16 v[198:201], v[214:217], v[16:19], v[198:201]
	v_mfma_f32_16x16x32_bf16 v[114:117], v[214:217], v[28:31], v[114:117]
	ds_read_b128 v[214:217], v135 offset:4544
	s_waitcnt lgkmcnt(3)
	v_mfma_f32_16x16x32_bf16 v[210:213], v[222:225], v[16:19], v[210:213]
	v_mfma_f32_16x16x32_bf16 v[222:225], v[222:225], v[28:31], v[122:125]
	ds_read_b128 v[230:233], v135 offset:8896
	s_waitcnt lgkmcnt(3)
	v_mfma_f32_16x16x32_bf16 v[218:221], v[226:229], v[16:19], v[218:221]
	v_mfma_f32_16x16x32_bf16 v[194:197], v[226:229], v[28:31], v[194:197]
	ds_read_b128 v[234:237], v135 offset:13248
	s_waitcnt lgkmcnt(3)
	v_mfma_f32_16x16x32_bf16 v[226:229], v[206:209], v[20:23], v[118:121]
	v_mfma_f32_16x16x32_bf16 v[206:209], v[206:209], v[32:35], v[110:113]
	s_waitcnt lgkmcnt(2)
	v_mfma_f32_16x16x32_bf16 v[198:201], v[214:217], v[20:23], v[198:201]
	v_mfma_f32_16x16x32_bf16 v[214:217], v[214:217], v[32:35], v[114:117]
	s_waitcnt lgkmcnt(1)
	v_mfma_f32_16x16x32_bf16 v[122:125], v[230:233], v[20:23], v[210:213]
	v_mfma_f32_16x16x32_bf16 v[118:121], v[230:233], v[32:35], v[222:225]
	s_waitcnt lgkmcnt(0)
	v_mfma_f32_16x16x32_bf16 v[114:117], v[234:237], v[20:23], v[218:221]
	v_mfma_f32_16x16x32_bf16 v[110:113], v[234:237], v[32:35], v[194:197]
	ds_read2st64_b32 v[238:239], v139 offset0:68 offset1:70
	ds_read2st64_b32 v[240:241], v139 offset0:72 offset1:74
	ds_read2st64_b32 v[242:243], v139 offset0:100 offset1:102
	ds_read2st64_b32 v[244:245], v139 offset0:104 offset1:106
	ds_read2st64_b32 v[246:247], v139 offset0:132 offset1:134
	ds_read2st64_b32 v[248:249], v139 offset0:136 offset1:138
	ds_read2st64_b32 v[250:251], v139 offset0:164 offset1:166
	ds_read2st64_b32 v[252:253], v139 offset0:168 offset1:170
	s_nop 2
	v_fma_f32 v194, -v226, s4, v90
	v_fma_f32 v195, -v227, s4, v91
	v_pk_fma_f32 v[196:197], v[206:207], s[4:5], v[128:129] op_sel_hi:[1,0,1] neg_lo:[1,0,0] neg_hi:[1,0,0]
	v_exp_f32_e32 v194, v194
	v_exp_f32_e32 v195, v195
	v_exp_f32_e32 v196, v196
	v_exp_f32_e32 v197, v197
	v_pk_add_f32 v[194:195], v[194:195], 1.0 op_sel_hi:[1,0]
	v_pk_fma_f32 v[210:211], v[228:229], s[4:5], v[90:91] op_sel_hi:[1,0,1] neg_lo:[1,0,0] neg_hi:[1,0,0]
	v_rcp_f32_e32 v194, v194
	v_rcp_f32_e32 v195, v195
	v_pk_add_f32 v[196:197], v[196:197], 1.0 op_sel_hi:[1,0]
	v_pk_fma_f32 v[198:199], v[198:199], s[4:5], v[90:91] op_sel_hi:[1,0,1] neg_lo:[1,0,0] neg_hi:[1,0,0]
	v_rcp_f32_e32 v196, v196
	v_pk_mul_f32 v[194:195], v[130:131], v[194:195]
	v_rcp_f32_e32 v197, v197
	v_exp_f32_e32 v194, v194
	v_exp_f32_e32 v195, v195
	v_exp_f32_e32 v198, v198
	v_exp_f32_e32 v199, v199
	v_pk_fma_f32 v[200:201], v[200:201], s[4:5], v[90:91] op_sel_hi:[1,0,1] neg_lo:[1,0,0] neg_hi:[1,0,0]
	v_pk_fma_f32 v[202:203], v[194:195], v[194:195], 1.0 op_sel_hi:[1,1,0] neg_lo:[1,0,0] neg_hi:[1,0,0]
	v_exp_f32_e32 v200, v200
	v_sqrt_f32_e32 v202, v202
	v_sqrt_f32_e32 v203, v203
	v_exp_f32_e32 v201, v201
	v_pk_fma_f32 v[122:123], v[122:123], s[4:5], v[90:91] op_sel_hi:[1,0,1] neg_lo:[1,0,0] neg_hi:[1,0,0]
	v_pk_fma_f32 v[118:119], v[118:119], s[4:5], v[128:129] op_sel_hi:[1,0,1] neg_lo:[1,0,0] neg_hi:[1,0,0]
	v_pk_mul_f32 v[196:197], v[196:197], v[202:203]
	v_exp_f32_e32 v202, v210
	v_exp_f32_e32 v203, v211
	s_waitcnt lgkmcnt(0)
	v_pk_mul_f32 v[196:197], v[238:239], v[196:197]
	ds_write2st64_b32 v139, v194, v195 offset0:196 offset1:198
	ds_write2st64_b32 v140, v196, v197 offset1:2
	v_exp_f32_e32 v122, v122
	v_pk_add_f32 v[194:195], v[202:203], 1.0 op_sel_hi:[1,0]
	v_pk_fma_f32 v[202:203], v[208:209], s[4:5], v[128:129] op_sel_hi:[1,0,1] neg_lo:[1,0,0] neg_hi:[1,0,0]
	v_rcp_f32_e32 v194, v194
	v_rcp_f32_e32 v195, v195
	v_exp_f32_e32 v202, v202
	v_exp_f32_e32 v203, v203
	v_pk_mul_f32 v[194:195], v[130:131], v[194:195]
	v_exp_f32_e32 v123, v123
	v_exp_f32_e32 v194, v194
	v_exp_f32_e32 v195, v195
	v_pk_add_f32 v[202:203], v[202:203], 1.0 op_sel_hi:[1,0]
	v_pk_add_f32 v[122:123], v[122:123], 1.0 op_sel_hi:[1,0]
	v_rcp_f32_e32 v202, v202
	v_pk_fma_f32 v[206:207], v[194:195], v[194:195], 1.0 op_sel_hi:[1,1,0] neg_lo:[1,0,0] neg_hi:[1,0,0]
	v_rcp_f32_e32 v203, v203
	v_sqrt_f32_e32 v206, v206
	v_sqrt_f32_e32 v207, v207
	v_rcp_f32_e32 v122, v122
	v_rcp_f32_e32 v123, v123
	v_exp_f32_e32 v118, v118
	v_pk_mul_f32 v[202:203], v[202:203], v[206:207]
	v_exp_f32_e32 v119, v119
	v_pk_mul_f32 v[202:203], v[240:241], v[202:203]
	ds_write2st64_b32 v139, v194, v195 offset0:200 offset1:202
	ds_write2st64_b32 v142, v202, v203 offset1:2
	v_pk_add_f32 v[194:195], v[198:199], 1.0 op_sel_hi:[1,0]
	v_pk_fma_f32 v[198:199], v[214:215], s[4:5], v[128:129] op_sel_hi:[1,0,1] neg_lo:[1,0,0] neg_hi:[1,0,0]
	v_rcp_f32_e32 v194, v194
	v_rcp_f32_e32 v195, v195
	v_exp_f32_e32 v198, v198
	v_exp_f32_e32 v199, v199
	v_pk_mul_f32 v[194:195], v[130:131], v[194:195]
	v_pk_mul_f32 v[122:123], v[130:131], v[122:123]
	v_exp_f32_e32 v194, v194
	v_exp_f32_e32 v195, v195
	v_pk_add_f32 v[198:199], v[198:199], 1.0 op_sel_hi:[1,0]
	v_exp_f32_e32 v122, v122
	v_rcp_f32_e32 v198, v198
	v_pk_fma_f32 v[202:203], v[194:195], v[194:195], 1.0 op_sel_hi:[1,1,0] neg_lo:[1,0,0] neg_hi:[1,0,0]
	v_rcp_f32_e32 v199, v199
	v_sqrt_f32_e32 v202, v202
	v_sqrt_f32_e32 v203, v203
	v_exp_f32_e32 v123, v123
	v_pk_add_f32 v[118:119], v[118:119], 1.0 op_sel_hi:[1,0]
	v_pk_fma_f32 v[124:125], v[124:125], s[4:5], v[90:91] op_sel_hi:[1,0,1] neg_lo:[1,0,0] neg_hi:[1,0,0]
	v_pk_mul_f32 v[198:199], v[198:199], v[202:203]
	v_rcp_f32_e32 v118, v118
	v_pk_mul_f32 v[198:199], v[242:243], v[198:199]
	ds_write2st64_b32 v139, v194, v195 offset0:228 offset1:230
	ds_write2st64_b32 v144, v198, v199 offset1:2
	v_pk_add_f32 v[194:195], v[200:201], 1.0 op_sel_hi:[1,0]
	v_pk_fma_f32 v[198:199], v[216:217], s[4:5], v[128:129] op_sel_hi:[1,0,1] neg_lo:[1,0,0] neg_hi:[1,0,0]
	v_rcp_f32_e32 v194, v194
	v_rcp_f32_e32 v195, v195
	v_exp_f32_e32 v198, v198
	v_exp_f32_e32 v199, v199
	v_pk_mul_f32 v[194:195], v[130:131], v[194:195]
	v_rcp_f32_e32 v119, v119
	v_exp_f32_e32 v194, v194
	v_exp_f32_e32 v195, v195
	v_pk_add_f32 v[198:199], v[198:199], 1.0 op_sel_hi:[1,0]
	v_exp_f32_e32 v124, v124
	v_rcp_f32_e32 v198, v198
	v_pk_fma_f32 v[200:201], v[194:195], v[194:195], 1.0 op_sel_hi:[1,1,0] neg_lo:[1,0,0] neg_hi:[1,0,0]
	v_rcp_f32_e32 v199, v199
	v_sqrt_f32_e32 v200, v200
	v_sqrt_f32_e32 v201, v201
	v_exp_f32_e32 v125, v125
	v_pk_fma_f32 v[114:115], v[114:115], s[4:5], v[90:91] op_sel_hi:[1,0,1] neg_lo:[1,0,0] neg_hi:[1,0,0]
	v_pk_fma_f32 v[120:121], v[120:121], s[4:5], v[128:129] op_sel_hi:[1,0,1] neg_lo:[1,0,0] neg_hi:[1,0,0]
	v_pk_mul_f32 v[198:199], v[198:199], v[200:201]
	v_exp_f32_e32 v114, v114
	v_pk_mul_f32 v[198:199], v[198:199], v[244:245]
	ds_write2st64_b32 v139, v194, v195 offset0:232 offset1:234
	ds_write2st64_b32 v146, v198, v199 offset1:2
	v_pk_fma_f32 v[194:195], v[122:123], v[122:123], 1.0 op_sel_hi:[1,1,0] neg_lo:[1,0,0] neg_hi:[1,0,0]
	v_sqrt_f32_e32 v194, v194
	v_sqrt_f32_e32 v195, v195
	ds_write2st64_b32 v148, v122, v123 offset1:2
	v_exp_f32_e32 v115, v115
	v_pk_mul_f32 v[118:119], v[118:119], v[194:195]
	v_exp_f32_e32 v120, v120
	v_pk_mul_f32 v[118:119], v[118:119], v[246:247]
	ds_write2st64_b32 v150, v118, v119 offset1:2
	v_pk_add_f32 v[118:119], v[124:125], 1.0 op_sel_hi:[1,0]
	v_exp_f32_e32 v121, v121
	v_rcp_f32_e32 v118, v118
	v_rcp_f32_e32 v119, v119
	v_pk_add_f32 v[114:115], v[114:115], 1.0 op_sel_hi:[1,0]
	v_pk_add_f32 v[120:121], v[120:121], 1.0 op_sel_hi:[1,0]
	v_rcp_f32_e32 v114, v114
	v_pk_mul_f32 v[118:119], v[130:131], v[118:119]
	v_rcp_f32_e32 v115, v115
	v_exp_f32_e32 v118, v118
	v_exp_f32_e32 v119, v119
	v_rcp_f32_e32 v120, v120
	v_rcp_f32_e32 v121, v121
	v_pk_fma_f32 v[122:123], v[118:119], v[118:119], 1.0 op_sel_hi:[1,1,0] neg_lo:[1,0,0] neg_hi:[1,0,0]
	v_pk_fma_f32 v[110:111], v[110:111], s[4:5], v[128:129] op_sel_hi:[1,0,1] neg_lo:[1,0,0] neg_hi:[1,0,0]
	v_sqrt_f32_e32 v122, v122
	v_sqrt_f32_e32 v123, v123
	v_pk_mul_f32 v[114:115], v[130:131], v[114:115]
	v_exp_f32_e32 v110, v110
	v_exp_f32_e32 v111, v111
	v_exp_f32_e32 v114, v114
	v_exp_f32_e32 v115, v115
	v_pk_mul_f32 v[120:121], v[120:121], v[122:123]
	ds_write2st64_b32 v152, v118, v119 offset1:2
	v_pk_mul_f32 v[120:121], v[120:121], v[248:249]
	ds_write2st64_b32 v154, v120, v121 offset1:2
	v_pk_add_f32 v[110:111], v[110:111], 1.0 op_sel_hi:[1,0]
	v_pk_fma_f32 v[118:119], v[114:115], v[114:115], 1.0 op_sel_hi:[1,1,0] neg_lo:[1,0,0] neg_hi:[1,0,0]
	v_rcp_f32_e32 v110, v110
	v_rcp_f32_e32 v111, v111
	v_sqrt_f32_e32 v118, v118
	v_sqrt_f32_e32 v119, v119
	v_pk_fma_f32 v[116:117], v[116:117], s[4:5], v[90:91] op_sel_hi:[1,0,1] neg_lo:[1,0,0] neg_hi:[1,0,0]
	ds_write2st64_b32 v156, v114, v115 offset1:2
	v_exp_f32_e32 v116, v116
	v_exp_f32_e32 v117, v117
	v_pk_mul_f32 v[110:111], v[110:111], v[118:119]
	v_pk_fma_f32 v[112:113], v[112:113], s[4:5], v[128:129] op_sel_hi:[1,0,1] neg_lo:[1,0,0] neg_hi:[1,0,0]
	v_pk_mul_f32 v[110:111], v[110:111], v[250:251]
	ds_write2st64_b32 v158, v110, v111 offset1:2
	v_pk_add_f32 v[110:111], v[116:117], 1.0 op_sel_hi:[1,0]
	v_exp_f32_e32 v112, v112
	v_rcp_f32_e32 v110, v110
	v_rcp_f32_e32 v111, v111
	v_exp_f32_e32 v113, v113
	v_pk_mul_f32 v[110:111], v[130:131], v[110:111]
	s_nop 0
	v_exp_f32_e32 v110, v110
	v_exp_f32_e32 v111, v111
	v_pk_add_f32 v[112:113], v[112:113], 1.0 op_sel_hi:[1,0]
	v_pk_fma_f32 v[114:115], v[110:111], v[110:111], 1.0 op_sel_hi:[1,1,0] neg_lo:[1,0,0] neg_hi:[1,0,0]
	v_rcp_f32_e32 v112, v112
	v_rcp_f32_e32 v113, v113
	v_sqrt_f32_e32 v114, v114
	v_sqrt_f32_e32 v115, v115
	s_nop 0
	v_pk_mul_f32 v[112:113], v[112:113], v[114:115]
	v_pk_mul_f32 v[112:113], v[112:113], v[252:253]
	ds_write2st64_b32 v160, v110, v111 offset1:2
	ds_write2st64_b32 v162, v112, v113 offset1:2
	s_waitcnt lgkmcnt(0)
	s_barrier
	ds_read2st64_b32 v[110:111], v164 offset0:196 offset1:198
	ds_read2st64_b32 v[112:113], v164 offset0:200 offset1:202
	ds_read_b32 v88, v165
	ds_read_b32 v109, v166
	ds_read_b32 v114, v167
	ds_read_b32 v115, v168
	ds_read_b32 v116, v169
	ds_read_b32 v117, v170
	ds_read_b32 v118, v171
	ds_read_b32 v119, v172
	s_waitcnt lgkmcnt(7)
	v_fmac_f32_e32 v88, 0, v110
	s_waitcnt lgkmcnt(6)
	v_fmac_f32_e32 v109, v88, v111
	v_mul_f32_e32 v88, v110, v111
	ds_read2st64_b32 v[110:111], v164 offset0:204 offset1:206
	s_waitcnt lgkmcnt(6)
	v_fmac_f32_e32 v114, v109, v112
	v_mul_f32_e32 v88, v88, v112
	s_waitcnt lgkmcnt(5)
	v_fmac_f32_e32 v115, v114, v113
	v_mul_f32_e32 v88, v88, v113
	ds_read2st64_b32 v[112:113], v164 offset0:208 offset1:210
	s_waitcnt lgkmcnt(1)
	v_fmac_f32_e32 v116, v115, v110
	v_mul_f32_e32 v88, v88, v110
	v_fmac_f32_e32 v117, v116, v111
	v_mul_f32_e32 v88, v88, v111
	s_waitcnt lgkmcnt(0)
	v_fmac_f32_e32 v118, v117, v112
	v_mul_f32_e32 v88, v88, v112
	v_fmac_f32_e32 v119, v118, v113
	v_mul_f32_e32 v88, v88, v113
	ds_read2st64_b32 v[110:111], v164 offset0:212 offset1:214
	ds_read2st64_b32 v[112:113], v164 offset0:216 offset1:218
	ds_read_b32 v109, v173
	ds_read_b32 v114, v174
	ds_read_b32 v115, v175
	ds_read_b32 v116, v176
	ds_read_b32 v117, v177
	ds_read_b32 v118, v178
	ds_read_b32 v120, v179
	ds_read_b32 v121, v180
	s_waitcnt lgkmcnt(7)
	v_fmac_f32_e32 v109, v119, v110
	v_mul_f32_e32 v88, v88, v110
	s_waitcnt lgkmcnt(6)
	v_fmac_f32_e32 v114, v109, v111
	v_mul_f32_e32 v88, v88, v111
	ds_read2st64_b32 v[110:111], v164 offset0:220 offset1:222
	s_waitcnt lgkmcnt(6)
	v_fmac_f32_e32 v115, v114, v112
	v_mul_f32_e32 v88, v88, v112
	s_waitcnt lgkmcnt(5)
	v_fmac_f32_e32 v116, v115, v113
	v_mul_f32_e32 v88, v88, v113
	ds_read2st64_b32 v[112:113], v164 offset0:224 offset1:226
	s_waitcnt lgkmcnt(1)
	v_mul_f32_e32 v88, v88, v110
	v_fmac_f32_e32 v117, v116, v110
	v_mul_f32_e32 v88, v88, v111
	v_fmac_f32_e32 v118, v117, v111
	s_waitcnt lgkmcnt(0)
	v_mul_f32_e32 v88, v88, v112
	v_fmac_f32_e32 v120, v118, v112
	v_mul_f32_e32 v88, v88, v113
	v_fmac_f32_e32 v121, v120, v113
	ds_write_b32 v136, v88
	ds_write_b32 v137, v121
	s_waitcnt lgkmcnt(0)
	s_barrier
	s_and_saveexec_b64 s[0:1], vcc
	s_cbranch_execz .LBB0_282
	ds_read_b32 v88, v181
	ds_read_b32 v109, v182
	ds_read_b32 v110, v183
	ds_read_b32 v111, v184
	ds_read_b32 v112, v185
	ds_read_b32 v113, v186
	ds_read_b32 v114, v187
	ds_read_b32 v115, v189
	s_and_b32 s5, s2, 0x60
	s_add_i32 s5, s5, s87
	s_waitcnt lgkmcnt(6)
	v_fmac_f32_e32 v109, 0, v88
	s_waitcnt lgkmcnt(5)
	v_mul_f32_e32 v88, v88, v110
	s_and_b32 s6, s2, 0x80
	s_waitcnt lgkmcnt(3)
	v_mul_f32_e32 v88, v88, v112
	s_add_i32 s5, s5, s6
	v_fmac_f32_e32 v111, v109, v110
	s_waitcnt lgkmcnt(1)
	v_mul_f32_e32 v109, v88, v114
	v_lshl_or_b32 v88, s5, 10, v190
	v_fmac_f32_e32 v113, v111, v112
	v_lshlrev_b64 v[110:111], 2, v[88:89]
	s_waitcnt lgkmcnt(0)
	v_fmac_f32_e32 v115, v113, v114
	v_lshl_add_u64 v[112:113], s[80:81], 0, v[110:111]
	v_lshl_add_u64 v[110:111], s[82:83], 0, v[110:111]
	s_waitcnt vmcnt(0)
	global_store_dword v[112:113], v109, off sc0 sc1
	global_store_dword v[110:111], v115, off sc0 sc1
	s_or_b64 exec, exec, s[0:1]
	s_add_i32 s2, s2, 32
	s_addk_i32 s3, 0x800
	s_cmpk_lg_i32 s2, 0x100
	s_cbranch_scc0 .LBB0_303
	s_branch .Llru1_waited

.LBB0_646:
	s_waitcnt lgkmcnt(0)
	s_barrier
	ds_read_b128 v[120:123], v154
	ds_read_b128 v[124:127], v154 offset:4352
	ds_read_b128 v[132:135], v154 offset:8704
	ds_read_b128 v[216:219], v154 offset:13056
	s_waitcnt lgkmcnt(3)
	v_mfma_f32_16x16x32_bf16 v[128:131], v[120:123], v[0:3], 0
	v_mfma_f32_16x16x32_bf16 v[120:123], v[120:123], v[8:11], 0
	ds_read_b128 v[224:227], v154 offset:64
	s_waitcnt lgkmcnt(3)
	v_mfma_f32_16x16x32_bf16 v[220:223], v[124:127], v[0:3], 0
	v_mfma_f32_16x16x32_bf16 v[124:127], v[124:127], v[8:11], 0
	ds_read_b128 v[232:235], v154 offset:4416
	s_waitcnt lgkmcnt(3)
	v_mfma_f32_16x16x32_bf16 v[228:231], v[132:135], v[0:3], 0
	v_mfma_f32_16x16x32_bf16 v[132:135], v[132:135], v[8:11], 0
	ds_read_b128 v[240:243], v154 offset:8768
	s_waitcnt lgkmcnt(3)
	v_mfma_f32_16x16x32_bf16 v[236:239], v[216:219], v[0:3], 0
	v_mfma_f32_16x16x32_bf16 v[216:219], v[216:219], v[8:11], 0
	ds_read_b128 v[244:247], v154 offset:13120
	s_waitcnt lgkmcnt(3)
	v_mfma_f32_16x16x32_bf16 v[128:131], v[224:227], v[4:7], v[128:131]
	v_mfma_f32_16x16x32_bf16 v[120:123], v[224:227], v[12:15], v[120:123]
	ds_read_b128 v[224:227], v154 offset:128
	s_waitcnt lgkmcnt(3)
	v_mfma_f32_16x16x32_bf16 v[220:223], v[232:235], v[4:7], v[220:223]
	v_mfma_f32_16x16x32_bf16 v[124:127], v[232:235], v[12:15], v[124:127]
	ds_read_b128 v[232:235], v154 offset:4480
	s_waitcnt lgkmcnt(3)
	v_mfma_f32_16x16x32_bf16 v[228:231], v[240:243], v[4:7], v[228:231]
	v_mfma_f32_16x16x32_bf16 v[132:135], v[240:243], v[12:15], v[132:135]
	ds_read_b128 v[240:243], v154 offset:8832
	s_waitcnt lgkmcnt(3)
	v_mfma_f32_16x16x32_bf16 v[236:239], v[244:247], v[4:7], v[236:239]
	v_mfma_f32_16x16x32_bf16 v[216:219], v[244:247], v[12:15], v[216:219]
	ds_read_b128 v[244:247], v154 offset:13184
	s_waitcnt lgkmcnt(3)
	v_mfma_f32_16x16x32_bf16 v[128:131], v[224:227], v[16:19], v[128:131]
	v_mfma_f32_16x16x32_bf16 v[120:123], v[224:227], v[24:27], v[120:123]
	ds_read_b128 v[224:227], v154 offset:192
	s_waitcnt lgkmcnt(3)
	v_mfma_f32_16x16x32_bf16 v[220:223], v[232:235], v[16:19], v[220:223]
	v_mfma_f32_16x16x32_bf16 v[124:127], v[232:235], v[24:27], v[124:127]
	ds_read_b128 v[232:235], v154 offset:4544
	s_waitcnt lgkmcnt(3)
	v_mfma_f32_16x16x32_bf16 v[228:231], v[240:243], v[16:19], v[228:231]
	v_mfma_f32_16x16x32_bf16 v[240:243], v[240:243], v[24:27], v[132:135]
	ds_read_b128 v[248:251], v154 offset:8896
	s_waitcnt lgkmcnt(3)
	v_mfma_f32_16x16x32_bf16 v[236:239], v[244:247], v[16:19], v[236:239]
	v_mfma_f32_16x16x32_bf16 v[216:219], v[244:247], v[24:27], v[216:219]
	ds_read_b128 v[162:165], v154 offset:13248
	s_waitcnt lgkmcnt(3)
	v_mfma_f32_16x16x32_bf16 v[244:247], v[224:227], v[20:23], v[128:131]
	v_mfma_f32_16x16x32_bf16 v[224:227], v[224:227], v[28:31], v[120:123]
	s_waitcnt lgkmcnt(2)
	v_mfma_f32_16x16x32_bf16 v[220:223], v[232:235], v[20:23], v[220:223]
	v_mfma_f32_16x16x32_bf16 v[232:235], v[232:235], v[28:31], v[124:127]
	s_waitcnt lgkmcnt(1)
	v_mfma_f32_16x16x32_bf16 v[132:135], v[248:251], v[20:23], v[228:231]
	v_mfma_f32_16x16x32_bf16 v[128:131], v[248:251], v[28:31], v[240:243]
	s_waitcnt lgkmcnt(0)
	v_mfma_f32_16x16x32_bf16 v[124:127], v[162:165], v[20:23], v[236:239]
	v_mfma_f32_16x16x32_bf16 v[120:123], v[162:165], v[28:31], v[216:219]
	ds_read2st64_b32 v[240:241], v159 offset0:68 offset1:70
	ds_read2st64_b32 v[242:243], v159 offset0:72 offset1:74
	ds_read2st64_b32 v[248:249], v159 offset0:100 offset1:102
	ds_read2st64_b32 v[250:251], v159 offset0:104 offset1:106
	v_fma_f32 v110, -v244, s16, v138
	v_fma_f32 v111, -v245, s16, v139
	v_pk_fma_f32 v[162:163], v[224:225], s[16:17], v[140:141] op_sel_hi:[1,0,1] neg_lo:[1,0,0] neg_hi:[1,0,0]
	v_exp_f32_e32 v110, v110
	v_exp_f32_e32 v111, v111
	v_exp_f32_e32 v162, v162
	v_exp_f32_e32 v163, v163
	v_pk_add_f32 v[110:111], v[110:111], 1.0 op_sel_hi:[1,0]
	v_pk_fma_f32 v[218:219], v[246:247], s[16:17], v[138:139] op_sel_hi:[1,0,1] neg_lo:[1,0,0] neg_hi:[1,0,0]
	v_rcp_f32_e32 v110, v110
	v_rcp_f32_e32 v111, v111
	v_pk_add_f32 v[162:163], v[162:163], 1.0 op_sel_hi:[1,0]
	v_pk_fma_f32 v[132:133], v[132:133], s[16:17], v[138:139] op_sel_hi:[1,0,1] neg_lo:[1,0,0] neg_hi:[1,0,0]
	v_rcp_f32_e32 v162, v162
	v_pk_mul_f32 v[110:111], v[142:143], v[110:111]
	v_rcp_f32_e32 v163, v163
	v_exp_f32_e32 v110, v110
	v_exp_f32_e32 v111, v111
	v_exp_f32_e32 v132, v132
	v_exp_f32_e32 v133, v133
	v_pk_fma_f32 v[128:129], v[128:129], s[16:17], v[140:141] op_sel_hi:[1,0,1] neg_lo:[1,0,0] neg_hi:[1,0,0]
	v_pk_fma_f32 v[164:165], v[110:111], v[110:111], 1.0 op_sel_hi:[1,1,0] neg_lo:[1,0,0] neg_hi:[1,0,0]
	v_exp_f32_e32 v128, v128
	v_sqrt_f32_e32 v164, v164
	v_sqrt_f32_e32 v165, v165
	v_exp_f32_e32 v129, v129
	v_pk_fma_f32 v[124:125], v[124:125], s[16:17], v[138:139] op_sel_hi:[1,0,1] neg_lo:[1,0,0] neg_hi:[1,0,0]
	v_pk_fma_f32 v[120:121], v[120:121], s[16:17], v[140:141] op_sel_hi:[1,0,1] neg_lo:[1,0,0] neg_hi:[1,0,0]
	v_pk_mul_f32 v[162:163], v[162:163], v[164:165]
	v_exp_f32_e32 v164, v218
	v_exp_f32_e32 v165, v219
	s_waitcnt lgkmcnt(0)
	v_pk_mul_f32 v[162:163], v[240:241], v[162:163]
	ds_write2st64_b32 v159, v110, v111 offset0:196 offset1:198
	v_pk_add_f32 v[110:111], v[164:165], 1.0 op_sel_hi:[1,0]
	v_pk_fma_f32 v[164:165], v[226:227], s[16:17], v[140:141] op_sel_hi:[1,0,1] neg_lo:[1,0,0] neg_hi:[1,0,0]
	v_rcp_f32_e32 v110, v110
	v_rcp_f32_e32 v111, v111
	v_exp_f32_e32 v164, v164
	v_exp_f32_e32 v165, v165
	v_pk_add_f32 v[128:129], v[128:129], 1.0 op_sel_hi:[1,0]
	v_pk_mul_f32 v[110:111], v[142:143], v[110:111]
	v_rcp_f32_e32 v128, v128
	v_exp_f32_e32 v110, v110
	v_exp_f32_e32 v111, v111
	v_pk_add_f32 v[164:165], v[164:165], 1.0 op_sel_hi:[1,0]
	v_rcp_f32_e32 v129, v129
	v_rcp_f32_e32 v164, v164
	v_pk_fma_f32 v[216:217], v[110:111], v[110:111], 1.0 op_sel_hi:[1,1,0] neg_lo:[1,0,0] neg_hi:[1,0,0]
	v_rcp_f32_e32 v165, v165
	v_sqrt_f32_e32 v216, v216
	v_sqrt_f32_e32 v217, v217
	v_exp_f32_e32 v124, v124
	v_exp_f32_e32 v125, v125
	v_exp_f32_e32 v120, v120
	v_pk_mul_f32 v[164:165], v[164:165], v[216:217]
	v_pk_fma_f32 v[216:217], v[220:221], s[16:17], v[138:139] op_sel_hi:[1,0,1] neg_lo:[1,0,0] neg_hi:[1,0,0]
	v_pk_mul_f32 v[164:165], v[242:243], v[164:165]
	v_exp_f32_e32 v216, v216
	v_exp_f32_e32 v217, v217
	ds_write2st64_b32 v159, v110, v111 offset0:200 offset1:202
	ds_write2st64_b32 v215, v164, v165 offset1:2
	v_pk_fma_f32 v[164:165], v[232:233], s[16:17], v[140:141] op_sel_hi:[1,0,1] neg_lo:[1,0,0] neg_hi:[1,0,0]
	v_pk_add_f32 v[110:111], v[216:217], 1.0 op_sel_hi:[1,0]
	v_exp_f32_e32 v164, v164
	v_rcp_f32_e32 v110, v110
	v_rcp_f32_e32 v111, v111
	v_exp_f32_e32 v165, v165
	v_exp_f32_e32 v121, v121
	v_pk_mul_f32 v[110:111], v[142:143], v[110:111]
	s_nop 0
	v_exp_f32_e32 v110, v110
	v_exp_f32_e32 v111, v111
	v_pk_add_f32 v[164:165], v[164:165], 1.0 op_sel_hi:[1,0]
	v_pk_add_f32 v[120:121], v[120:121], 1.0 op_sel_hi:[1,0]
	v_rcp_f32_e32 v164, v164
	v_pk_fma_f32 v[216:217], v[110:111], v[110:111], 1.0 op_sel_hi:[1,1,0] neg_lo:[1,0,0] neg_hi:[1,0,0]
	v_rcp_f32_e32 v165, v165
	v_sqrt_f32_e32 v216, v216
	v_sqrt_f32_e32 v217, v217
	v_rcp_f32_e32 v120, v120
	v_rcp_f32_e32 v121, v121
	v_pk_mul_f32 v[164:165], v[164:165], v[216:217]
	v_pk_fma_f32 v[216:217], v[222:223], s[16:17], v[138:139] op_sel_hi:[1,0,1] neg_lo:[1,0,0] neg_hi:[1,0,0]
	v_pk_mul_f32 v[164:165], v[248:249], v[164:165]
	v_exp_f32_e32 v216, v216
	v_exp_f32_e32 v217, v217
	ds_write2st64_b32 v159, v110, v111 offset0:228 offset1:230
	ds_write2st64_b32 v253, v164, v165 offset1:2
	v_pk_fma_f32 v[164:165], v[234:235], s[16:17], v[140:141] op_sel_hi:[1,0,1] neg_lo:[1,0,0] neg_hi:[1,0,0]
	v_pk_add_f32 v[110:111], v[216:217], 1.0 op_sel_hi:[1,0]
	v_exp_f32_e32 v164, v164
	v_rcp_f32_e32 v110, v110
	v_rcp_f32_e32 v111, v111
	v_exp_f32_e32 v165, v165
	v_pk_mul_f32 v[110:111], v[142:143], v[110:111]
	s_nop 0
	v_exp_f32_e32 v110, v110
	v_exp_f32_e32 v111, v111
	v_pk_add_f32 v[164:165], v[164:165], 1.0 op_sel_hi:[1,0]
	v_pk_fma_f32 v[216:217], v[110:111], v[110:111], 1.0 op_sel_hi:[1,1,0] neg_lo:[1,0,0] neg_hi:[1,0,0]
	v_rcp_f32_e32 v164, v164
	v_rcp_f32_e32 v165, v165
	v_sqrt_f32_e32 v216, v216
	v_sqrt_f32_e32 v217, v217
	s_nop 0
	v_pk_mul_f32 v[164:165], v[164:165], v[216:217]
	v_pk_mul_f32 v[164:165], v[164:165], v[250:251]
	ds_read2st64_b32 v[240:241], v159 offset0:132 offset1:134
	ds_read2st64_b32 v[242:243], v159 offset0:136 offset1:138
	ds_read2st64_b32 v[248:249], v159 offset0:164 offset1:166
	ds_read2st64_b32 v[250:251], v159 offset0:168 offset1:170
	ds_write2st64_b32 v159, v110, v111 offset0:232 offset1:234
	ds_write2st64_b32 v166, v164, v165 offset1:2
	v_pk_add_f32 v[110:111], v[132:133], 1.0 op_sel_hi:[1,0]
	v_rcp_f32_e32 v110, v110
	v_rcp_f32_e32 v111, v111
	ds_write2st64_b32 v160, v162, v163 offset1:2
	v_pk_mul_f32 v[110:111], v[142:143], v[110:111]
	s_nop 0
	v_exp_f32_e32 v110, v110
	v_exp_f32_e32 v111, v111
	s_nop 0
	v_pk_fma_f32 v[132:133], v[110:111], v[110:111], 1.0 op_sel_hi:[1,1,0] neg_lo:[1,0,0] neg_hi:[1,0,0]
	s_nop 0
	v_sqrt_f32_e32 v132, v132
	v_sqrt_f32_e32 v133, v133
	s_nop 0
	v_pk_mul_f32 v[128:129], v[128:129], v[132:133]
	v_pk_fma_f32 v[132:133], v[134:135], s[16:17], v[138:139] op_sel_hi:[1,0,1] neg_lo:[1,0,0] neg_hi:[1,0,0]
	s_waitcnt lgkmcnt(3)
	v_pk_mul_f32 v[128:129], v[128:129], v[240:241]
	v_exp_f32_e32 v132, v132
	v_exp_f32_e32 v133, v133
	ds_write2st64_b32 v168, v110, v111 offset1:2
	ds_write2st64_b32 v170, v128, v129 offset1:2
	v_pk_fma_f32 v[128:129], v[130:131], s[16:17], v[140:141] op_sel_hi:[1,0,1] neg_lo:[1,0,0] neg_hi:[1,0,0]
	v_pk_add_f32 v[110:111], v[132:133], 1.0 op_sel_hi:[1,0]
	s_nop 0
	v_rcp_f32_e32 v110, v110
	v_rcp_f32_e32 v111, v111
	v_exp_f32_e32 v128, v128
	v_exp_f32_e32 v129, v129
	v_pk_mul_f32 v[110:111], v[142:143], v[110:111]
	v_pk_add_f32 v[128:129], v[128:129], 1.0 op_sel_hi:[1,0]
	v_exp_f32_e32 v110, v110
	v_exp_f32_e32 v111, v111
	v_rcp_f32_e32 v128, v128
	v_rcp_f32_e32 v129, v129
	v_pk_fma_f32 v[130:131], v[110:111], v[110:111], 1.0 op_sel_hi:[1,1,0] neg_lo:[1,0,0] neg_hi:[1,0,0]
	s_nop 0
	v_sqrt_f32_e32 v130, v130
	v_sqrt_f32_e32 v131, v131
	s_nop 0
	v_pk_mul_f32 v[128:129], v[128:129], v[130:131]
	v_pk_mul_f32 v[128:129], v[128:129], v[242:243]
	ds_write2st64_b32 v172, v110, v111 offset1:2
	ds_write2st64_b32 v174, v128, v129 offset1:2
	v_pk_add_f32 v[110:111], v[124:125], 1.0 op_sel_hi:[1,0]
	v_rcp_f32_e32 v110, v110
	v_rcp_f32_e32 v111, v111
	s_nop 0
	v_pk_mul_f32 v[110:111], v[142:143], v[110:111]
	s_nop 0
	v_exp_f32_e32 v110, v110
	v_exp_f32_e32 v111, v111
	s_nop 0
	v_pk_fma_f32 v[124:125], v[110:111], v[110:111], 1.0 op_sel_hi:[1,1,0] neg_lo:[1,0,0] neg_hi:[1,0,0]
	s_nop 0
	v_sqrt_f32_e32 v124, v124
	v_sqrt_f32_e32 v125, v125
	s_nop 0
	v_pk_mul_f32 v[120:121], v[120:121], v[124:125]
	v_pk_fma_f32 v[124:125], v[126:127], s[16:17], v[138:139] op_sel_hi:[1,0,1] neg_lo:[1,0,0] neg_hi:[1,0,0]
	v_pk_mul_f32 v[120:121], v[120:121], v[248:249]
	v_exp_f32_e32 v124, v124
	v_exp_f32_e32 v125, v125
	ds_write2st64_b32 v176, v110, v111 offset1:2
	ds_write2st64_b32 v178, v120, v121 offset1:2
	v_pk_fma_f32 v[120:121], v[122:123], s[16:17], v[140:141] op_sel_hi:[1,0,1] neg_lo:[1,0,0] neg_hi:[1,0,0]
	v_pk_add_f32 v[110:111], v[124:125], 1.0 op_sel_hi:[1,0]
	s_nop 0
	v_rcp_f32_e32 v110, v110
	v_rcp_f32_e32 v111, v111
	v_exp_f32_e32 v120, v120
	v_exp_f32_e32 v121, v121
	v_pk_mul_f32 v[110:111], v[142:143], v[110:111]
	v_pk_add_f32 v[120:121], v[120:121], 1.0 op_sel_hi:[1,0]
	v_exp_f32_e32 v110, v110
	v_exp_f32_e32 v111, v111
	v_rcp_f32_e32 v120, v120
	v_rcp_f32_e32 v121, v121
	v_pk_fma_f32 v[122:123], v[110:111], v[110:111], 1.0 op_sel_hi:[1,1,0] neg_lo:[1,0,0] neg_hi:[1,0,0]
	s_nop 0
	v_sqrt_f32_e32 v122, v122
	v_sqrt_f32_e32 v123, v123
	s_nop 0
	v_pk_mul_f32 v[120:121], v[120:121], v[122:123]
	v_pk_mul_f32 v[120:121], v[120:121], v[250:251]
	ds_write2st64_b32 v180, v110, v111 offset1:2
	ds_write2st64_b32 v182, v120, v121 offset1:2
	s_waitcnt lgkmcnt(0)
	s_barrier
	ds_read2st64_b32 v[110:111], v184 offset0:196 offset1:198
	ds_read2st64_b32 v[120:121], v184 offset0:200 offset1:202
	ds_read_b32 v88, v185
	ds_read_b32 v109, v186
	ds_read_b32 v122, v187
	ds_read_b32 v123, v189
	ds_read_b32 v124, v190
	ds_read_b32 v125, v191
	ds_read_b32 v126, v192
	ds_read_b32 v127, v193
	s_waitcnt lgkmcnt(7)
	v_fmac_f32_e32 v88, 0, v110
	s_waitcnt lgkmcnt(6)
	v_fmac_f32_e32 v109, v88, v111
	v_mul_f32_e32 v88, v110, v111
	ds_read2st64_b32 v[110:111], v184 offset0:204 offset1:206
	s_waitcnt lgkmcnt(6)
	v_fmac_f32_e32 v122, v109, v120
	v_mul_f32_e32 v88, v88, v120
	s_waitcnt lgkmcnt(5)
	v_fmac_f32_e32 v123, v122, v121
	v_mul_f32_e32 v88, v88, v121
	ds_read2st64_b32 v[120:121], v184 offset0:208 offset1:210
	s_waitcnt lgkmcnt(1)
	v_fmac_f32_e32 v124, v123, v110
	v_mul_f32_e32 v88, v88, v110
	v_fmac_f32_e32 v125, v124, v111
	v_mul_f32_e32 v88, v88, v111
	s_waitcnt lgkmcnt(0)
	v_fmac_f32_e32 v126, v125, v120
	v_mul_f32_e32 v88, v88, v120
	v_fmac_f32_e32 v127, v126, v121
	v_mul_f32_e32 v88, v88, v121
	ds_read2st64_b32 v[110:111], v184 offset0:212 offset1:214
	ds_read2st64_b32 v[120:121], v184 offset0:216 offset1:218
	ds_read_b32 v109, v194
	ds_read_b32 v122, v195
	ds_read_b32 v123, v196
	ds_read_b32 v124, v197
	ds_read_b32 v125, v198
	ds_read_b32 v126, v199
	ds_read_b32 v128, v200
	ds_read_b32 v129, v201
	s_waitcnt lgkmcnt(7)
	v_fmac_f32_e32 v109, v127, v110
	v_mul_f32_e32 v88, v88, v110
	s_waitcnt lgkmcnt(6)
	v_fmac_f32_e32 v122, v109, v111
	v_mul_f32_e32 v88, v88, v111
	ds_read2st64_b32 v[110:111], v184 offset0:220 offset1:222
	s_waitcnt lgkmcnt(6)
	v_fmac_f32_e32 v123, v122, v120
	v_mul_f32_e32 v88, v88, v120
	s_waitcnt lgkmcnt(5)
	v_fmac_f32_e32 v124, v123, v121
	v_mul_f32_e32 v88, v88, v121
	ds_read2st64_b32 v[120:121], v184 offset0:224 offset1:226
	s_waitcnt lgkmcnt(1)
	v_mul_f32_e32 v88, v88, v110
	v_fmac_f32_e32 v125, v124, v110
	v_mul_f32_e32 v88, v88, v111
	v_fmac_f32_e32 v126, v125, v111
	s_waitcnt lgkmcnt(0)
	v_mul_f32_e32 v88, v88, v120
	v_fmac_f32_e32 v128, v126, v120
	v_mul_f32_e32 v88, v88, v121
	v_fmac_f32_e32 v129, v128, v121
	ds_write_b32 v155, v88
	ds_write_b32 v156, v129
	s_waitcnt lgkmcnt(0)
	s_barrier
	ds_read_b32 v88, v212
	s_and_saveexec_b64 s[2:3], s[0:1]
	s_cbranch_execnz .LBB0_652
	s_or_b64 exec, exec, s[2:3]
	s_and_saveexec_b64 s[2:3], s[4:5]
	s_cbranch_execnz .LBB0_653
